# ctx-query attention units moved to RG-LRU workgroups
# speedup vs baseline: 1.0032x; 1.0032x over previous
.LBB0_692:
	s_and_b64 vcc, exec, s[4:5]
	s_cbranch_vccz .LBB0_783
	s_and_b32 s0, s22, 0x7fffffc0
	s_cmpk_lg_i32 s0, 0x100
	s_mov_b64 s[4:5], -1
	s_cbranch_scc0 .LBB0_745
	s_cmpk_lt_u32 s22, 0x200
	s_cbranch_scc1 .LBB0_744
	s_add_i32 s0, s22, 0xfffffe00
	v_mbcnt_lo_u32_b32 v0, -1, 0
	v_mbcnt_hi_u32_b32 v0, -1, v0
	s_lshr_b32 s4, s0, 5
	v_add_u32_e32 v36, s93, v0
	s_lshl_b32 s0, s22, 8
	s_lshl_b32 s12, s4, 11
	v_readfirstlane_b32 s2, v36
	s_and_b32 s0, s0, 0x700
	s_ashr_i32 s5, s2, 6
	s_or_b32 s0, s12, s0
	s_lshl_b32 s2, s5, 5
	v_readlane_b32 s8, v255, 11
	v_and_b32_e32 v0, 31, v36
	s_add_i32 s0, s2, s0
	v_readlane_b32 s9, v255, 12
	s_bfe_u32 s1, s22, 0x20003
	v_or_b32_e32 v4, s0, v0
	v_mov_b64_e32 v[2:3], s[8:9]
	v_bfe_u32 v37, v36, 5, 1
	v_mad_i64_i32 v[2:3], s[2:3], v4, s72, v[2:3]
	s_lshl_b32 s36, s1, 8
	v_lshl_add_u64 v[2:3], v[2:3], 0, s[36:37]
	v_lshlrev_b32_e32 v34, 4, v37
	v_mov_b32_e32 v35, v1
	v_lshl_add_u64 v[30:31], v[2:3], 0, v[34:35]
	global_load_dwordx4 v[2:5], v[30:31], off offset:2560
	global_load_dwordx4 v[6:9], v[30:31], off offset:2592
	global_load_dwordx4 v[10:13], v[30:31], off offset:2624
	global_load_dwordx4 v[14:17], v[30:31], off offset:2656
	global_load_dwordx4 v[18:21], v[30:31], off offset:2688
	global_load_dwordx4 v[22:25], v[30:31], off offset:2720
	global_load_dwordx4 v[26:29], v[30:31], off offset:2752
	s_nop 0
	global_load_dwordx4 v[30:33], v[30:31], off offset:2784
	v_lshlrev_b32_e32 v35, 4, v36
	v_and_b32_e32 v42, 0xf0, v35
	s_movk_i32 s6, 0x60
	v_bitop3_b32 v215, v34, v42, s6 bitop3:0x36
	s_movk_i32 s6, 0x80
	v_bitop3_b32 v216, v34, v42, s6 bitop3:0x36
	s_movk_i32 s6, 0xa0
	v_bitop3_b32 v217, v34, v42, s6 bitop3:0x36
	s_movk_i32 s6, 0xc0
	s_lshl_b32 s2, s5, 9
	s_lshl_b32 s3, s5, 13
	v_bitop3_b32 v218, v34, v42, s6 bitop3:0x36
	s_movk_i32 s6, 0xe0
	s_lshl_b32 s13, s4, 8
	v_bfe_u32 v38, v36, 4, 2
	v_bfe_u32 v39, v36, 2, 3
	v_bitop3_b32 v219, v34, v42, s6 bitop3:0x36
	s_lshl_b32 s6, s5, 3
	s_add_i32 s15, s3, 0
	s_add_i32 s14, s2, 0
	s_lshl_b32 s1, s1, 7
	s_add_i32 s13, s13, 0x8000
	v_lshlrev_b32_e32 v41, 3, v36
	v_or_b32_e32 v43, s6, v38
	v_or_b32_e32 v39, s6, v39
	s_add_i32 s15, s15, 0x11000
	s_add_i32 s14, s14, 0x10000
	s_movk_i32 s2, 0xb00
	v_and_b32_e32 v40, 32, v36
	v_lshlrev_b32_e32 v212, 8, v0
	v_bitop3_b32 v0, v37, v36, 15 bitop3:0x78
	v_and_b32_e32 v37, 24, v41
	v_bitop3_b32 v38, s6, v36, v38 bitop3:0x36
	v_mul_lo_u32 v39, v39, s2
	v_mul_lo_u32 v44, v43, s2
	v_bitop3_b32 v43, v43, v36, 4 bitop3:0x36
	s_add_u32 s36, s8, s36
	v_lshlrev_b32_e32 v38, 3, v38
	v_or3_b32 v37, v40, v37, v39
	s_movk_i32 s2, 0x78
	v_lshlrev_b32_e32 v39, 3, v43
	s_addc_u32 s38, s9, 0
	s_mul_i32 s4, s4, 0xb00000
	v_and_or_b32 v38, v38, s2, v44
	v_lshlrev_b32_e32 v196, 1, v37
	v_and_or_b32 v37, v39, s2, v44
	s_mul_hi_u32 s3, s12, 0x1600
	s_add_u32 s2, s36, s4
	v_add_u32_e32 v45, s15, v212
	s_addc_u32 s3, s38, s3
	s_lshl_b32 s6, s5, 11
	v_bitop3_b32 v213, v34, v42, 32 bitop3:0x36
	v_bitop3_b32 v214, v34, v42, 64 bitop3:0x36
	v_lshl_add_u32 v40, v0, 4, v45
	v_lshlrev_b32_e32 v0, 1, v38
	s_add_u32 s4, s2, 0x1200
	v_add_u32_e32 v43, v45, v213
	v_add_u32_e32 v46, v45, v214
	v_add_u32_e32 v47, v45, v215
	v_add_u32_e32 v48, v45, v216
	v_add_u32_e32 v49, v45, v217
	v_add_u32_e32 v50, v45, v218
	v_add_u32_e32 v45, v45, v219
	s_waitcnt vmcnt(7)
	ds_write_b128 v40, v[2:5]
	s_waitcnt vmcnt(6)
	ds_write_b128 v43, v[6:9]
	s_waitcnt vmcnt(5)
	ds_write_b128 v46, v[10:13]
	s_waitcnt vmcnt(4)
	ds_write_b128 v47, v[14:17]
	s_waitcnt vmcnt(3)
	ds_write_b128 v48, v[18:21]
	s_waitcnt vmcnt(2)
	ds_write_b128 v49, v[22:25]
	s_waitcnt vmcnt(1)
	ds_write_b128 v50, v[26:29]
	s_waitcnt vmcnt(0)
	ds_write_b128 v45, v[30:33]
	s_addc_u32 s5, s3, 0
	v_lshl_add_u64 v[2:3], s[2:3], 0, v[0:1]
	s_add_i32 s39, s6, 0
	v_lshl_add_u32 v198, v37, 1, v249
	v_lshl_add_u64 v[2:3], v[2:3], 0, s[26:27]
	s_add_i32 m0, s39, 0x8000
	v_mov_b32_e32 v199, v1
	global_load_lds_dwordx4 v[2:3], off
	s_mov_b32 m0, s39
	v_lshl_add_u64 v[2:3], s[2:3], 0, v[198:199]
	global_load_lds_dwordx4 v196, s[4:5]
	v_lshl_add_u64 v[2:3], v[2:3], 0, s[26:27]
	s_add_i32 m0, s39, 0x8400
	v_or_b32_e32 v200, 0x80, v196
	global_load_lds_dwordx4 v[2:3], off
	s_add_i32 m0, s39, 0x400
	v_or_b32_e32 v2, 32, v34
	global_load_lds_dwordx4 v200, s[4:5]
	v_lshlrev_b32_e32 v9, 1, v36
	v_and_b32_e32 v11, 0x118, v41
	v_or_b32_e32 v3, 64, v34
	v_or_b32_e32 v4, 0x60, v34
	v_or_b32_e32 v5, 0x80, v34
	v_or_b32_e32 v6, 0xa0, v34
	v_or_b32_e32 v7, 0xc0, v34
	v_or_b32_e32 v8, 0xe0, v34
	v_and_b32_e32 v10, 0xc0, v35
	s_waitcnt vmcnt(0)
	s_movk_i32 s2, 0xf0
	v_bitop3_b32 v222, v2, v212, v42 bitop3:0xde
	v_and_or_b32 v2, v9, 32, v11
	v_mov_b32_e32 v16, v1
	v_mov_b32_e32 v17, v1
	v_bitop3_b32 v220, v34, v35, s2 bitop3:0x78
	v_bitop3_b32 v221, v34, v212, v42 bitop3:0xde
	v_bitop3_b32 v223, v3, v212, v42 bitop3:0xde
	v_bitop3_b32 v224, v4, v212, v42 bitop3:0xde
	v_bitop3_b32 v225, v5, v212, v42 bitop3:0xde
	v_bitop3_b32 v226, v6, v212, v42 bitop3:0xde
	v_bitop3_b32 v227, v7, v212, v42 bitop3:0xde
	v_bitop3_b32 v228, v8, v212, v42 bitop3:0xde
	v_add3_u32 v229, v10, 0, v2
	v_mov_b32_e32 v2, v1
	v_mov_b32_e32 v3, v1
	v_mov_b32_e32 v4, v1
	v_mov_b32_e32 v5, v1
	v_mov_b32_e32 v6, v1
	v_mov_b32_e32 v7, v1
	v_mov_b32_e32 v8, v1
	v_mov_b32_e32 v9, v1
	v_mov_b32_e32 v10, v1
	v_mov_b32_e32 v11, v1
	v_mov_b32_e32 v12, v1
	v_mov_b32_e32 v13, v1
	v_mov_b32_e32 v14, v1
	v_mov_b32_e32 v15, v1
	v_mov_b64_e32 v[80:81], v[16:17]
	v_mov_b64_e32 v[48:49], v[16:17]
	v_mov_b64_e32 v[32:33], v[16:17]
	v_mov_b64_e32 v[128:129], v[16:17]
	v_mov_b64_e32 v[112:113], v[16:17]
	v_mov_b64_e32 v[96:97], v[16:17]
	v_mov_b64_e32 v[64:65], v[16:17]
	v_mov_b32_e32 v197, v1
	v_mov_b32_e32 v201, v1
	s_mov_b32 s40, 0
	v_mov_b32_e32 v202, v1
	v_mov_b32_e32 v203, v1
	v_mov_b32_e32 v231, 0
	s_mov_b64 s[4:5], 0
	s_mov_b64 s[6:7], -1
	v_mov_b64_e32 v[78:79], v[14:15]
	v_mov_b64_e32 v[76:77], v[12:13]
	v_mov_b64_e32 v[74:75], v[10:11]
	v_mov_b64_e32 v[72:73], v[8:9]
	v_mov_b64_e32 v[70:71], v[6:7]
	v_mov_b64_e32 v[68:69], v[4:5]
	v_mov_b64_e32 v[66:67], v[2:3]
	v_mov_b64_e32 v[46:47], v[14:15]
	v_mov_b64_e32 v[44:45], v[12:13]
	v_mov_b64_e32 v[42:43], v[10:11]
	v_mov_b64_e32 v[40:41], v[8:9]
	v_mov_b64_e32 v[38:39], v[6:7]
	v_mov_b64_e32 v[36:37], v[4:5]
	v_mov_b64_e32 v[34:35], v[2:3]
	v_mov_b64_e32 v[30:31], v[14:15]
	v_mov_b64_e32 v[28:29], v[12:13]
	v_mov_b64_e32 v[26:27], v[10:11]
	v_mov_b64_e32 v[24:25], v[8:9]
	v_mov_b64_e32 v[22:23], v[6:7]
	v_mov_b64_e32 v[20:21], v[4:5]
	v_mov_b64_e32 v[18:19], v[2:3]
	v_mov_b64_e32 v[126:127], v[14:15]
	v_mov_b64_e32 v[124:125], v[12:13]
	v_mov_b64_e32 v[122:123], v[10:11]
	v_mov_b64_e32 v[120:121], v[8:9]
	v_mov_b64_e32 v[118:119], v[6:7]
	v_mov_b64_e32 v[116:117], v[4:5]
	v_mov_b64_e32 v[114:115], v[2:3]
	v_mov_b64_e32 v[110:111], v[14:15]
	v_mov_b64_e32 v[108:109], v[12:13]
	v_mov_b64_e32 v[106:107], v[10:11]
	v_mov_b64_e32 v[104:105], v[8:9]
	v_mov_b64_e32 v[102:103], v[6:7]
	v_mov_b64_e32 v[100:101], v[4:5]
	v_mov_b64_e32 v[98:99], v[2:3]
	v_mov_b64_e32 v[94:95], v[14:15]
	v_mov_b64_e32 v[92:93], v[12:13]
	v_mov_b64_e32 v[90:91], v[10:11]
	v_mov_b64_e32 v[88:89], v[8:9]
	v_mov_b64_e32 v[86:87], v[6:7]
	v_mov_b64_e32 v[84:85], v[4:5]
	v_mov_b64_e32 v[82:83], v[2:3]
	v_mov_b64_e32 v[62:63], v[14:15]
	v_mov_b64_e32 v[60:61], v[12:13]
	v_mov_b64_e32 v[58:59], v[10:11]
	v_mov_b64_e32 v[56:57], v[8:9]
	v_mov_b64_e32 v[54:55], v[6:7]
	v_mov_b64_e32 v[52:53], v[4:5]
	v_mov_b64_e32 v[50:51], v[2:3]
	v_mov_b32_e32 v230, 0
	s_waitcnt vmcnt(0) lgkmcnt(0)
	s_barrier
	s_branch .LBB0_699
